# on top of v2: rs_prep issues its 8 row-partial loads together (one exposed latency instead of two), 5 instances
# speedup vs baseline: 1.0042x; 1.0042x over previous
; #define PG8_LAS __attribute__((address_space(3)))
;     __device__ __forceinline__ void prep(const Unit& u, int parity, PG8_LAS unsigned char* lds, int tid) const { rs_prep(ss, u.pm, parity, lds, tid); }
;     __device__ __forceinline__ void prep(const Unit& u, int parity, PG8_LAS unsigned char* lds, int tid) const { rs_prep(ss, u.pm, parity, lds, tid); }
;     __device__ __forceinline__ void prep(const Unit& u, int parity, PG8_LAS unsigned char* lds, int tid) const { rs_prep(ss, u.pm, parity, lds, tid); }
;     __device__ __forceinline__ void prep(const Unit& u, int parity, PG8_LAS unsigned char* lds, int tid) const { rs_prep(ss, u.pm, parity, lds, tid); }
; __device__ __forceinline__ void rs_prep(const float* ss, int pm, int parity, PG8_LAS unsigned char* lds, int tid) {
;     if (tid < 256) {
;         const f32x4* p = (const f32x4*)(ss + (size_t)(pm * BM + tid) * 32);
;         f32x4 s = p[0];
; #pragma unroll
;         for (int j = 1; j < 8; ++j) s += p[j];
;         const float tot = (s[0] + s[1]) + (s[2] + s[3]);
;         *(PG8_LAS float*)(lds + RS_OFF + parity * 1024 + tid * 4) = __builtin_amdgcn_rsqf(tot * (1.0f / 2048.0f) + 1e-6f);
;     }
; template <class Epi, class Sched, bool ALIGN_EPI = false, bool SP2 = false>
; __device__ __forceinline__ void gemm_phase(PG8_LAS unsigned char* lds, const Gemm g, const Sched& S, const Epi& E, const int wave_id) {
;     ...
;         if constexpr (Epi::HAS_PREP) { if (newpanel) E.prep(nxt, tp ^ 1, lds, tid); }
.LBB0_177:
	s_cmp_lg_u32 s14, s40
	s_cselect_b64 s[20:21], -1, 0
	s_and_b64 s[42:43], s[38:39], s[20:21]
	s_andn2_b64 vcc, exec, s[42:43]
	s_cbranch_vccnz .LBB0_181
	s_and_saveexec_b64 s[42:43], s[36:37]
	s_cbranch_execz .LBB0_180
	v_lshl_add_u32 v142, s14, 8, v1
	v_ashrrev_i32_e32 v143, 31, v142
	v_lshlrev_b64 v[142:143], 7, v[142:143]
	v_lshl_add_u64 v[158:159], s[2:3], 0, v[142:143]
	global_load_dwordx4 v[142:145], v[158:159], off offset:48
	global_load_dwordx4 v[146:149], v[158:159], off offset:32
	global_load_dwordx4 v[150:153], v[158:159], off
	global_load_dwordx4 v[154:157], v[158:159], off offset:16
	global_load_dwordx4 v[178:181], v[158:159], off offset:112
	global_load_dwordx4 v[182:185], v[158:159], off offset:96
	global_load_dwordx4 v[186:189], v[158:159], off offset:80
	global_load_dwordx4 v[190:193], v[158:159], off offset:64
	s_waitcnt vmcnt(4)
	v_pk_add_f32 v[152:153], v[152:153], v[156:157]
	v_pk_add_f32 v[150:151], v[150:151], v[154:155]
	v_pk_add_f32 v[148:149], v[152:153], v[148:149]
	v_pk_add_f32 v[146:147], v[150:151], v[146:147]
	v_pk_add_f32 v[160:161], v[148:149], v[144:145]
	v_pk_add_f32 v[162:163], v[146:147], v[142:143]
	s_waitcnt vmcnt(0)
	v_pk_add_f32 v[192:193], v[160:161], v[192:193]
	v_pk_add_f32 v[190:191], v[162:163], v[190:191]
	v_pk_add_f32 v[188:189], v[192:193], v[188:189]
	v_pk_add_f32 v[186:187], v[190:191], v[186:187]
	v_pk_add_f32 v[184:185], v[188:189], v[184:185]
	v_pk_add_f32 v[182:183], v[186:187], v[182:183]
	v_pk_add_f32 v[180:181], v[184:185], v[180:181]
	v_pk_add_f32 v[178:179], v[182:183], v[178:179]
	s_nop 0
	v_pk_mov_b32 v[182:183], v[178:179], v[180:181] op_sel:[1,0]
	v_mov_b32_e32 v179, v181
	v_pk_add_f32 v[178:179], v[182:183], v[178:179]
	s_nop 0
	v_add_f32_e32 v178, v178, v179
	v_fmamk_f32 v178, v178, 0x3a000000, v221
	v_rsq_f32_e32 v178, v178
	v_lshlrev_b32_e32 v179, 10, v176
	v_xor_b32_e32 v179, 0x400, v179
	v_add_u32_e32 v179, v172, v179
	ds_write_b32 v179, v178

; #define PG8_LAS __attribute__((address_space(3)))
;     __host__ __device__ bool next(int i, Unit& u) const { const bool ok = StaticOrder::next(i, u); u.lm = 0; u.ln = 0; return ok; }
;     __host__ __device__ bool next(int i, Unit& u) const {
;         if ((long)i * G + c >= nwg) return false;
;         const long L = rev ? (long)((nwg - 1 - c) / G - i) * G + c : (long)i * G + c;
;         int wgid = (int)L; { const int q = nwg / NXCD, r = nwg % NXCD, xcd = wgid % NXCD, off = wgid / NXCD; wgid = (xcd < r ? xcd * (q + 1) : r * (q + 1) + (xcd - r) * q) + off; }
;         const int nig = wgm * nN, gid = wgid / nig, fm = gid * wgm, gsz = (nM - fm) < wgm ? (nM - fm) : wgm;
;         u.pm = fm + ((wgid % nig) % gsz); u.pn = (wgid % nig) / gsz; u.lm = fixed ? 0 : u.pm; u.ln = fixed ? 0 : u.pn; return true;
; __device__ __forceinline__ void rs_prep(const float* ss, int pm, int parity, PG8_LAS unsigned char* lds, int tid) {
;     if (tid < 256) {
;         const f32x4* p = (const f32x4*)(ss + (size_t)(pm * BM + tid) * 32);
;         f32x4 s = p[0];
; #pragma unroll
;         for (int j = 1; j < 8; ++j) s += p[j];
;         const float tot = (s[0] + s[1]) + (s[2] + s[3]);
;         *(PG8_LAS float*)(lds + RS_OFF + parity * 1024 + tid * 4) = __builtin_amdgcn_rsqf(tot * (1.0f / 2048.0f) + 1e-6f);
;     }
.LBB0_629:
	s_andn2_b64 vcc, exec, s[2:3]
	s_cbranch_vccnz .LBB0_733
	v_readlane_b32 s2, v253, 50
	v_readlane_b32 s12, v254, 63
	v_readlane_b32 s3, v253, 51
	v_readlane_b32 s13, v252, 0
	v_readlane_b32 s14, v252, 1
	v_readlane_b32 s15, v252, 2
	s_mov_b32 s4, s2
	s_mov_b64 s[2:3], s[12:13]
	v_readlane_b32 s11, v253, 0
	s_mov_b64 s[8:9], s[14:15]
	s_ashr_i32 s26, s4, 3
	s_cmpk_gt_i32 s26, 0x15ff
	v_mbcnt_lo_u32_b32 v10, -1, 0
	v_mbcnt_hi_u32_b32 v10, -1, v10
	s_cbranch_scc1 .LBB0_653
	s_add_u32 s2, s8, 0x600000
	s_addc_u32 s3, s9, 0
	s_lshr_b32 s4, s26, 29
	s_add_i32 s4, s26, s4
	s_ashr_i32 s5, s4, 3
	s_and_b32 s4, s4, -8
	s_sub_i32 s4, s26, s4
	s_cmp_lt_i32 s4, 0
	s_movk_i32 s10, 0x2c1
	s_cselect_b32 s10, s10, 0x2c0
	s_mul_i32 s4, s4, s10
	s_add_i32 s4, s4, s5
	s_mul_hi_i32 s5, s4, 0x2e8ba2e9
	s_lshr_b32 s10, s5, 31
	s_ashr_i32 s5, s5, 6
	s_add_i32 s5, s5, s10
	s_lshl_b32 s12, s5, 3
	s_mulk_i32 s5, 0x160
	s_sub_i32 s10, s4, s5
	s_bfe_u32 s4, s10, 0x3001c
	s_add_i32 s4, s10, s4
	s_and_b32 s4, s4, 0xfff8
	s_sub_i32 s4, s10, s4
	s_sext_i32_i16 s4, s4
	v_lshl_add_u32 v1, s11, 6, v10
	s_add_i32 s40, s12, s4
	s_movk_i32 s4, 0x100
	v_cmp_gt_i32_e64 s[36:37], s4, v1
	s_and_saveexec_b64 s[4:5], s[36:37]
	s_cbranch_execz .LBB0_633
	v_lshl_add_u32 v2, s40, 8, v1
	v_ashrrev_i32_e32 v3, 31, v2
	v_lshlrev_b64 v[2:3], 7, v[2:3]
	v_lshl_add_u64 v[20:21], s[2:3], 0, v[2:3]
	global_load_dwordx4 v[2:5], v[20:21], off offset:48
	global_load_dwordx4 v[6:9], v[20:21], off offset:32
	global_load_dwordx4 v[12:15], v[20:21], off
	global_load_dwordx4 v[16:19], v[20:21], off offset:16
	global_load_dwordx4 v[26:29], v[20:21], off offset:112
	global_load_dwordx4 v[30:33], v[20:21], off offset:96
	global_load_dwordx4 v[34:37], v[20:21], off offset:80
	global_load_dwordx4 v[38:41], v[20:21], off offset:64
	s_waitcnt vmcnt(4)
	v_pk_add_f32 v[14:15], v[14:15], v[18:19]
	v_pk_add_f32 v[12:13], v[12:13], v[16:17]
	v_pk_add_f32 v[8:9], v[14:15], v[8:9]
	v_pk_add_f32 v[6:7], v[12:13], v[6:7]
	v_pk_add_f32 v[22:23], v[8:9], v[4:5]
	v_pk_add_f32 v[24:25], v[6:7], v[2:3]
	s_waitcnt vmcnt(0)
	v_pk_add_f32 v[40:41], v[22:23], v[40:41]
	v_pk_add_f32 v[38:39], v[24:25], v[38:39]
	v_pk_add_f32 v[36:37], v[40:41], v[36:37]
	v_pk_add_f32 v[34:35], v[38:39], v[34:35]
	v_pk_add_f32 v[32:33], v[36:37], v[32:33]
	v_pk_add_f32 v[30:31], v[34:35], v[30:31]
	v_pk_add_f32 v[28:29], v[32:33], v[28:29]
	v_pk_add_f32 v[26:27], v[30:31], v[26:27]
	s_nop 0
	v_pk_mov_b32 v[30:31], v[26:27], v[28:29] op_sel:[1,0]
	v_mov_b32_e32 v27, v29
	v_pk_add_f32 v[26:27], v[30:31], v[26:27]
	s_nop 0
	v_add_f32_e32 v26, v26, v27
	v_fmamk_f32 v26, v26, 0x3a000000, v221
	v_rsq_f32_e32 v26, v26
	v_lshl_add_u32 v27, v1, 2, 0
	v_add_u32_e32 v27, 0x20000, v27
	ds_write_b32 v27, v26

; #define PG8_LAS __attribute__((address_space(3)))
;     __device__ __forceinline__ void prep(const Unit& u, int parity, PG8_LAS unsigned char* lds, int tid) const { rs_prep(ss, u.pm, parity, lds, tid); }
;     __device__ __forceinline__ void prep(const Unit& u, int parity, PG8_LAS unsigned char* lds, int tid) const { rs_prep(ss, u.pm, parity, lds, tid); }
;     __device__ __forceinline__ void prep(const Unit& u, int parity, PG8_LAS unsigned char* lds, int tid) const { rs_prep(ss, u.pm, parity, lds, tid); }
;     __device__ __forceinline__ void prep(const Unit& u, int parity, PG8_LAS unsigned char* lds, int tid) const { rs_prep(ss, u.pm, parity, lds, tid); }
; __device__ __forceinline__ void rs_prep(const float* ss, int pm, int parity, PG8_LAS unsigned char* lds, int tid) {
;     if (tid < 256) {
;         const f32x4* p = (const f32x4*)(ss + (size_t)(pm * BM + tid) * 32);
;         f32x4 s = p[0];
; #pragma unroll
;         for (int j = 1; j < 8; ++j) s += p[j];
;         const float tot = (s[0] + s[1]) + (s[2] + s[3]);
;         *(PG8_LAS float*)(lds + RS_OFF + parity * 1024 + tid * 4) = __builtin_amdgcn_rsqf(tot * (1.0f / 2048.0f) + 1e-6f);
;     }
; template <class Epi, class Sched, bool ALIGN_EPI = false, bool SP2 = false>
; __device__ __forceinline__ void gemm_phase(PG8_LAS unsigned char* lds, const Gemm g, const Sched& S, const Epi& E, const int wave_id) {
;     ...
;         if constexpr (Epi::HAS_PREP) { if (newpanel) E.prep(nxt, tp ^ 1, lds, tid); }
.LBB0_644:
	s_cmp_lg_u32 s14, s40
	s_cselect_b64 s[20:21], -1, 0
	s_and_b64 s[42:43], s[38:39], s[20:21]
	s_andn2_b64 vcc, exec, s[42:43]
	s_cbranch_vccnz .LBB0_648
	s_and_saveexec_b64 s[42:43], s[36:37]
	s_cbranch_execz .LBB0_647
	v_lshl_add_u32 v144, s14, 8, v1
	v_ashrrev_i32_e32 v145, 31, v144
	v_lshlrev_b64 v[144:145], 7, v[144:145]
	v_lshl_add_u64 v[144:145], s[2:3], 0, v[144:145]
	global_load_dwordx4 v[158:161], v[144:145], off offset:48
	global_load_dwordx4 v[162:165], v[144:145], off offset:32
	global_load_dwordx4 v[166:169], v[144:145], off
	global_load_dwordx4 v[170:173], v[144:145], off offset:16
	global_load_dwordx4 v[178:181], v[144:145], off offset:112
	global_load_dwordx4 v[182:185], v[144:145], off offset:96
	global_load_dwordx4 v[186:189], v[144:145], off offset:80
	global_load_dwordx4 v[190:193], v[144:145], off offset:64
	s_waitcnt vmcnt(4)
	v_pk_add_f32 v[168:169], v[168:169], v[172:173]
	v_pk_add_f32 v[166:167], v[166:167], v[170:171]
	v_pk_add_f32 v[164:165], v[168:169], v[164:165]
	v_pk_add_f32 v[162:163], v[166:167], v[162:163]
	v_pk_add_f32 v[174:175], v[164:165], v[160:161]
	v_pk_add_f32 v[176:177], v[162:163], v[158:159]
	s_waitcnt vmcnt(0)
	v_pk_add_f32 v[144:145], v[174:175], v[192:193]
	v_pk_add_f32 v[190:191], v[176:177], v[190:191]
	v_pk_add_f32 v[144:145], v[144:145], v[188:189]
	v_pk_add_f32 v[186:187], v[190:191], v[186:187]
	v_pk_add_f32 v[144:145], v[144:145], v[184:185]
	v_pk_add_f32 v[182:183], v[186:187], v[182:183]
	v_pk_add_f32 v[144:145], v[144:145], v[180:181]
	v_pk_add_f32 v[178:179], v[182:183], v[178:179]
	s_nop 0
	v_pk_mov_b32 v[180:181], v[178:179], v[144:145] op_sel:[1,0]
	v_mov_b32_e32 v179, v145
	v_pk_add_f32 v[144:145], v[180:181], v[178:179]
	s_nop 0
	v_add_f32_e32 v142, v144, v145
	v_fmamk_f32 v142, v142, 0x3a000000, v221
	v_rsq_f32_e32 v142, v142
	v_lshlrev_b32_e32 v144, 10, v157
	v_xor_b32_e32 v144, 0x400, v144
	v_add_u32_e32 v144, v149, v144
	ds_write_b32 v144, v142

; #define PG8_LAS __attribute__((address_space(3)))
;     __device__ __forceinline__ void prep(const Unit& u, int parity, PG8_LAS unsigned char* lds, int tid) const { rs_prep(ss, u.pm, parity, lds, tid); }
;     __device__ __forceinline__ void prep(const Unit& u, int parity, PG8_LAS unsigned char* lds, int tid) const { rs_prep(ss, u.pm, parity, lds, tid); }
;     __device__ __forceinline__ void prep(const Unit& u, int parity, PG8_LAS unsigned char* lds, int tid) const { rs_prep(ss, u.pm, parity, lds, tid); }
;     __device__ __forceinline__ void prep(const Unit& u, int parity, PG8_LAS unsigned char* lds, int tid) const { rs_prep(ss, u.pm, parity, lds, tid); }
; __device__ __forceinline__ void rs_prep(const float* ss, int pm, int parity, PG8_LAS unsigned char* lds, int tid) {
;     if (tid < 256) {
;         const f32x4* p = (const f32x4*)(ss + (size_t)(pm * BM + tid) * 32);
;         f32x4 s = p[0];
; #pragma unroll
;         for (int j = 1; j < 8; ++j) s += p[j];
;         const float tot = (s[0] + s[1]) + (s[2] + s[3]);
;         *(PG8_LAS float*)(lds + RS_OFF + parity * 1024 + tid * 4) = __builtin_amdgcn_rsqf(tot * (1.0f / 2048.0f) + 1e-6f);
;     }
; template <class Epi, class Sched, bool ALIGN_EPI = false, bool SP2 = false>
; __device__ __forceinline__ void gemm_phase(PG8_LAS unsigned char* lds, const Gemm g, const Sched& S, const Epi& E, const int wave_id) {
;     ...
;     if constexpr (Epi::HAS_PREP) E.prep(cur, 0, lds, tid);
.LBB0_889:
	s_andn2_b64 vcc, exec, s[4:5]
	s_cbranch_vccnz .LBB0_932
	s_add_u32 s4, s14, 0xa00000
	v_lshl_add_u32 v1, s18, 6, v10
	s_movk_i32 s8, 0x100
	s_addc_u32 s5, s15, 0
	v_cmp_gt_i32_e64 s[36:37], s8, v1
	s_and_saveexec_b64 s[8:9], s[36:37]
	s_cbranch_execz .LBB0_892
	v_lshl_add_u32 v2, s48, 8, v1
	v_ashrrev_i32_e32 v3, 31, v2
	v_lshlrev_b64 v[2:3], 7, v[2:3]
	v_lshl_add_u64 v[20:21], s[4:5], 0, v[2:3]
	global_load_dwordx4 v[2:5], v[20:21], off offset:48
	global_load_dwordx4 v[6:9], v[20:21], off offset:32
	global_load_dwordx4 v[12:15], v[20:21], off
	global_load_dwordx4 v[16:19], v[20:21], off offset:16
	global_load_dwordx4 v[26:29], v[20:21], off offset:112
	global_load_dwordx4 v[30:33], v[20:21], off offset:96
	global_load_dwordx4 v[34:37], v[20:21], off offset:80
	global_load_dwordx4 v[38:41], v[20:21], off offset:64
	s_waitcnt vmcnt(4)
	v_pk_add_f32 v[14:15], v[14:15], v[18:19]
	v_pk_add_f32 v[12:13], v[12:13], v[16:17]
	v_pk_add_f32 v[8:9], v[14:15], v[8:9]
	v_pk_add_f32 v[6:7], v[12:13], v[6:7]
	v_pk_add_f32 v[22:23], v[8:9], v[4:5]
	v_pk_add_f32 v[24:25], v[6:7], v[2:3]
	s_waitcnt vmcnt(0)
	v_pk_add_f32 v[40:41], v[22:23], v[40:41]
	v_pk_add_f32 v[38:39], v[24:25], v[38:39]
	v_pk_add_f32 v[36:37], v[40:41], v[36:37]
	v_pk_add_f32 v[34:35], v[38:39], v[34:35]
	v_pk_add_f32 v[32:33], v[36:37], v[32:33]
	v_pk_add_f32 v[30:31], v[34:35], v[30:31]
	v_pk_add_f32 v[28:29], v[32:33], v[28:29]
	v_pk_add_f32 v[26:27], v[30:31], v[26:27]
	s_nop 0
	v_pk_mov_b32 v[30:31], v[26:27], v[28:29] op_sel:[1,0]
	v_mov_b32_e32 v27, v29
	v_pk_add_f32 v[26:27], v[30:31], v[26:27]
	s_nop 0
	v_add_f32_e32 v26, v26, v27
	v_fmamk_f32 v26, v26, 0x3a000000, v221
	v_rsq_f32_e32 v26, v26
	v_lshl_add_u32 v27, v1, 2, 0
	v_add_u32_e32 v27, 0x20000, v27
	ds_write_b32 v27, v26

; #define PG8_LAS __attribute__((address_space(3)))
;     __device__ __forceinline__ void prep(const Unit& u, int parity, PG8_LAS unsigned char* lds, int tid) const { rs_prep(ss, u.pm, parity, lds, tid); }
;     __device__ __forceinline__ void prep(const Unit& u, int parity, PG8_LAS unsigned char* lds, int tid) const { rs_prep(ss, u.pm, parity, lds, tid); }
;     __device__ __forceinline__ void prep(const Unit& u, int parity, PG8_LAS unsigned char* lds, int tid) const { rs_prep(ss, u.pm, parity, lds, tid); }
;     __device__ __forceinline__ void prep(const Unit& u, int parity, PG8_LAS unsigned char* lds, int tid) const { rs_prep(ss, u.pm, parity, lds, tid); }
; __device__ __forceinline__ void rs_prep(const float* ss, int pm, int parity, PG8_LAS unsigned char* lds, int tid) {
;     if (tid < 256) {
;         const f32x4* p = (const f32x4*)(ss + (size_t)(pm * BM + tid) * 32);
;         f32x4 s = p[0];
; #pragma unroll
;         for (int j = 1; j < 8; ++j) s += p[j];
;         const float tot = (s[0] + s[1]) + (s[2] + s[3]);
;         *(PG8_LAS float*)(lds + RS_OFF + parity * 1024 + tid * 4) = __builtin_amdgcn_rsqf(tot * (1.0f / 2048.0f) + 1e-6f);
;     }
; template <class Epi, class Sched, bool ALIGN_EPI = false, bool SP2 = false>
; __device__ __forceinline__ void gemm_phase(PG8_LAS unsigned char* lds, const Gemm g, const Sched& S, const Epi& E, const int wave_id) {
;     ...
;         if constexpr (Epi::HAS_PREP) { if (newpanel) E.prep(nxt, tp ^ 1, lds, tid); }
.LBB0_907:
	s_cmp_lg_u32 s20, s48
	s_cselect_b64 s[46:47], -1, 0
	s_and_b64 s[52:53], s[40:41], s[46:47]
	s_andn2_b64 vcc, exec, s[52:53]
	s_cbranch_vccnz .LBB0_911
	s_and_saveexec_b64 s[52:53], s[36:37]
	s_cbranch_execz .LBB0_910
	v_lshl_add_u32 v114, s20, 8, v1
	v_ashrrev_i32_e32 v115, 31, v114
	v_lshlrev_b64 v[114:115], 7, v[114:115]
	v_lshl_add_u64 v[138:139], s[4:5], 0, v[114:115]
	global_load_dwordx4 v[114:117], v[138:139], off offset:48
	global_load_dwordx4 v[118:121], v[138:139], off offset:32
	global_load_dwordx4 v[130:133], v[138:139], off
	global_load_dwordx4 v[134:137], v[138:139], off offset:16
	global_load_dwordx4 v[178:181], v[138:139], off offset:112
	global_load_dwordx4 v[182:185], v[138:139], off offset:96
	global_load_dwordx4 v[186:189], v[138:139], off offset:80
	global_load_dwordx4 v[190:193], v[138:139], off offset:64
	s_waitcnt vmcnt(4)
	v_pk_add_f32 v[132:133], v[132:133], v[136:137]
	v_pk_add_f32 v[130:131], v[130:131], v[134:135]
	v_pk_add_f32 v[120:121], v[132:133], v[120:121]
	v_pk_add_f32 v[118:119], v[130:131], v[118:119]
	v_pk_add_f32 v[140:141], v[120:121], v[116:117]
	v_pk_add_f32 v[142:143], v[118:119], v[114:115]
	s_waitcnt vmcnt(0)
	v_pk_add_f32 v[192:193], v[140:141], v[192:193]
	v_pk_add_f32 v[190:191], v[142:143], v[190:191]
	v_pk_add_f32 v[188:189], v[192:193], v[188:189]
	v_pk_add_f32 v[186:187], v[190:191], v[186:187]
	v_pk_add_f32 v[184:185], v[188:189], v[184:185]
	v_pk_add_f32 v[182:183], v[186:187], v[182:183]
	v_pk_add_f32 v[180:181], v[184:185], v[180:181]
	v_pk_add_f32 v[178:179], v[182:183], v[178:179]
	s_nop 0
	v_pk_mov_b32 v[182:183], v[178:179], v[180:181] op_sel:[1,0]
	v_mov_b32_e32 v179, v181
	v_pk_add_f32 v[178:179], v[182:183], v[178:179]
	s_nop 0
	v_add_f32_e32 v178, v178, v179
	v_fmamk_f32 v178, v178, 0x3a000000, v221
	v_rsq_f32_e32 v178, v178
	v_lshlrev_b32_e32 v179, 10, v245
	v_xor_b32_e32 v179, 0x400, v179
	v_add_u32_e32 v179, v239, v179
	ds_write_b32 v179, v178
